# SB unit: static priority raise for waves 4-7 (7.4), wave index read correctly
# baseline (speedup 1.0000x reference)
.LBB0_332:
	s_or_b64 exec, exec, s[2:3]
	s_waitcnt lgkmcnt(0)
	s_barrier
	ds_read_b32 v0, v229
	s_movk_i32 s2, 0x3ff
	s_waitcnt lgkmcnt(0)
	v_cmp_lt_i32_e32 vcc, s2, v0
	v_readfirstlane_b32 s97, v0
	s_mov_b64 s[2:3], -1
	s_cbranch_vccnz .LBB0_301
	s_cmpk_gt_i32 s97, 0x1ff
	s_cbranch_scc0 .LBB0_385
	v_readlane_b32 s2, v255, 10
	s_cmp_lt_u32 s2, 4
	s_cbranch_scc1 .Lsb_noprio
	s_setprio 1
